# best5 + k3 prologue de-serialisation: attn_skips' 12 serial load->wait steps replaced by 8 loads issued together up front
# speedup vs baseline: 1.0054x; 1.0006x over previous
; __device__ __forceinline__ int attn_skip(const Ctx& c, int l, int b, int h, int qb) {
;     const unsigned* nrm = (const unsigned*)(c.ws + WS_NORM) + (size_t)l * 128; const float* Fbh = (const float*)(c.ws + WS_FCUM) + (size_t)(b * NHEAD + h) * SEQ;
;     const float Bq = sqrtf(__uint_as_float(nrm[(b * NHEAD + h) * 2]) * __uint_as_float(nrm[(b * NHEAD + h) * 2 + 1]));
;     const int q0 = qb * QB, NT0 = (q0 + QB) / KVBLK; const float fq0 = Fbh[q0];
;     const bool cnd = (c.lane < NT0 - 4) && (2.f * Bq + fq0 - Fbh[64 * c.lane + 63] < -150.f);
;     return __builtin_amdgcn_readfirstlane(__popcll(__ballot(cnd))) & ~1;
; }
; __device__ __forceinline__ unsigned attn_skips(const Ctx& c, int l) {
;     unsigned pk = 0u;
; #pragma unroll
;     for (int i = 0; i < 4; ++i) { int b, h, qb; unit_of(c.vcu, i, b, h, qb); pk |= (unsigned)attn_skip(c, l, b, h, qb) << (8 * i); }
.LBB0_90:
	s_and_b64 vcc, exec, s[38:39]
	s_cbranch_vccz .LBB0_307
	s_ashr_i32 s81, s80, 31
	s_bfe_u32 s13, s24, 0x20003
	s_lshl_b64 s[16:17], s[80:81], 9
	v_readlane_b32 s0, v253, 19
	s_add_u32 s23, s0, s16
	v_readlane_b32 s0, v253, 20
	s_addc_u32 s92, s0, s17
	s_ashr_i32 s0, s24, 2
	s_and_b32 s6, s0, -8
	s_lshl_b32 s0, s24, 8
	s_and_b32 s16, s0, 0x700
	s_add_i32 s0, s16, 0x100
	s_lshr_b32 s0, s0, 6
	s_waitcnt vmcnt(0)
	v_lshlrev_b32_e32 v0, 6, v200
	s_add_i32 s0, s0, -4
	v_cmp_gt_u32_e32 vcc, s0, v200
	s_mov_b64 s[40:41], 0
	v_lshlrev_b32_e32 v209, 2, v0
	s_mov_b64 s[38:39], 0
	s_waitcnt lgkmcnt(0)
	s_or_b32 s98, s13, s6
	s_xor_b32 s99, s13, 7
	s_or_b32 s99, s99, s6
	s_lshl_b32 s20, s98, 3
	s_add_u32 s100, s23, s20
	s_addc_u32 s101, s92, 0
	global_load_dwordx2 v[184:185], v97, s[100:101]
	s_lshl_b32 s20, s99, 3
	s_add_u32 s100, s23, s20
	s_addc_u32 s101, s92, 0
	global_load_dwordx2 v[186:187], v97, s[100:101]
	s_lshl_b32 s20, s98, 14
	s_add_u32 s100, s4, s20
	s_addc_u32 s101, s5, 0
	global_load_dword v188, v209, s[100:101] offset:252
	s_lshl_b32 s20, s16, 2
	s_add_u32 s20, s100, s20
	s_addc_u32 s21, s101, 0
	global_load_dword v190, v97, s[20:21]
	s_xor_b32 s20, s16, 0xf00
	s_lshl_b32 s20, s20, 2
	s_add_u32 s20, s100, s20
	s_addc_u32 s21, s101, 0
	global_load_dword v192, v97, s[20:21]
	s_lshl_b32 s20, s99, 14
	s_add_u32 s100, s4, s20
	s_addc_u32 s101, s5, 0
	global_load_dword v189, v209, s[100:101] offset:252
	s_add_i32 s20, s16, 0x800
	s_lshl_b32 s20, s20, 2
	s_add_u32 s20, s100, s20
	s_addc_u32 s21, s101, 0
	global_load_dword v191, v97, s[20:21]
	s_xor_b32 s20, s16, 0x700
	s_lshl_b32 s20, s20, 2
	s_add_u32 s20, s100, s20
	s_addc_u32 s21, s101, 0
	global_load_dword v193, v97, s[20:21]
	s_and_saveexec_b64 s[42:43], vcc
	s_cbranch_execz .LBB0_93
	s_or_b32 s44, s13, s6
	s_lshl_b32 s20, s44, 1
	s_ashr_i32 s21, s20, 31
	s_lshl_b64 s[20:21], s[20:21], 2
	s_add_u32 s20, s23, s20
	s_addc_u32 s21, s92, s21
	s_waitcnt lgkmcnt(0)
	s_waitcnt vmcnt(0)
	v_mov_b32_e32 v0, v184
	v_mov_b32_e32 v1, v185
	s_ashr_i32 s45, s44, 31
	s_lshl_b64 s[20:21], s[44:45], 14
	s_add_u32 s20, s4, s20
	s_addc_u32 s21, s5, s21
	s_lshl_b32 s0, s16, 2
	s_waitcnt vmcnt(0)
	v_mul_f32_e32 v0, v0, v1
	v_cmp_gt_f32_e32 vcc, s87, v0
	v_mul_f32_e32 v1, 0x4f800000, v0
	s_nop 0
	v_cndmask_b32_e32 v0, v0, v1, vcc
	v_sqrt_f32_e32 v1, v0
	s_nop 0
	v_add_u32_e32 v2, -1, v1
	v_fma_f32 v3, -v2, v1, v0
	v_cmp_ge_f32_e64 s[38:39], 0, v3
	v_add_u32_e32 v3, 1, v1
	s_nop 0
	v_cndmask_b32_e64 v2, v1, v2, s[38:39]
	v_fma_f32 v1, -v3, v1, v0
	v_cmp_lt_f32_e64 s[38:39], 0, v1
	s_nop 1
	v_cndmask_b32_e64 v1, v2, v3, s[38:39]
	v_mul_f32_e32 v2, 0x37800000, v1
	v_cndmask_b32_e32 v1, v1, v2, vcc
	v_cmp_class_f32_e32 vcc, v0, v213
	s_nop 1
	v_cndmask_b32_e32 v0, v1, v0, vcc
	v_mov_b32_e32 v1, s0
	s_waitcnt vmcnt(0)
	v_mov_b32_e32 v1, v190
	s_waitcnt vmcnt(0)
	v_fmac_f32_e32 v1, 2.0, v0
	s_waitcnt vmcnt(0)
	v_mov_b32_e32 v0, v188
	s_waitcnt vmcnt(0)
	v_sub_f32_e32 v0, v1, v0
	v_cmp_gt_f32_e32 vcc, s93, v0
	s_and_b64 s[38:39], vcc, exec
.LBB0_93:
	s_or_b64 exec, exec, s[42:43]
	s_add_i32 s12, s16, 0x900
	v_cndmask_b32_e64 v0, 0, 1, s[38:39]
	s_lshr_b32 s12, s12, 6
	v_cmp_ne_u32_e32 vcc, 0, v0
	s_add_i32 s12, s12, -4
	s_xor_b32 s17, s13, 7
	s_bcnt1_i32_b64 s0, vcc
	v_cmp_gt_u32_e32 vcc, s12, v200
	s_and_saveexec_b64 s[42:43], vcc
	s_cbranch_execz .LBB0_95
	s_or_b32 s40, s17, s6
	s_lshl_b32 s20, s40, 1
	s_ashr_i32 s21, s20, 31
	s_lshl_b64 s[20:21], s[20:21], 2
	s_add_u32 s20, s23, s20
	s_addc_u32 s21, s92, s21
	s_waitcnt lgkmcnt(0)
	s_waitcnt vmcnt(0)
	v_mov_b32_e32 v0, v186
	v_mov_b32_e32 v1, v187
	s_ashr_i32 s41, s40, 31
	s_lshl_b64 s[20:21], s[40:41], 14
	s_add_u32 s20, s4, s20
	s_addc_u32 s21, s5, s21
	s_lshl_b32 s12, s16, 2
	s_waitcnt vmcnt(0)
	v_mul_f32_e32 v0, v0, v1
	v_cmp_gt_f32_e32 vcc, s87, v0
	v_mul_f32_e32 v1, 0x4f800000, v0
	s_nop 0
	v_cndmask_b32_e32 v0, v0, v1, vcc
	v_sqrt_f32_e32 v1, v0
	s_nop 0
	v_add_u32_e32 v2, -1, v1
	v_fma_f32 v3, -v2, v1, v0
	v_cmp_ge_f32_e64 s[38:39], 0, v3
	v_add_u32_e32 v3, 1, v1
	s_nop 0
	v_cndmask_b32_e64 v2, v1, v2, s[38:39]
	v_fma_f32 v1, -v3, v1, v0
	v_cmp_lt_f32_e64 s[38:39], 0, v1
	s_nop 1
	v_cndmask_b32_e64 v1, v2, v3, s[38:39]
	v_mul_f32_e32 v2, 0x37800000, v1
	s_add_u32 s38, s20, s12
	v_cndmask_b32_e32 v1, v1, v2, vcc
	v_cmp_class_f32_e32 vcc, v0, v213
	s_addc_u32 s39, s21, 0
	s_nop 0
	v_cndmask_b32_e32 v0, v1, v0, vcc
	s_waitcnt vmcnt(0)
	v_mov_b32_e32 v1, v191
	s_waitcnt vmcnt(0)
	v_fmac_f32_e32 v1, 2.0, v0
	s_waitcnt vmcnt(0)
	v_mov_b32_e32 v0, v189
	s_waitcnt vmcnt(0)
	v_sub_f32_e32 v0, v1, v0
	v_cmp_gt_f32_e32 vcc, s93, v0
	s_and_b64 s[40:41], vcc, exec
; __device__ __forceinline__ int attn_skip(const Ctx& c, int l, int b, int h, int qb) {
;     const unsigned* nrm = (const unsigned*)(c.ws + WS_NORM) + (size_t)l * 128; const float* Fbh = (const float*)(c.ws + WS_FCUM) + (size_t)(b * NHEAD + h) * SEQ;
;     const float Bq = sqrtf(__uint_as_float(nrm[(b * NHEAD + h) * 2]) * __uint_as_float(nrm[(b * NHEAD + h) * 2 + 1]));
;     const int q0 = qb * QB, NT0 = (q0 + QB) / KVBLK; const float fq0 = Fbh[q0];
;     const bool cnd = (c.lane < NT0 - 4) && (2.f * Bq + fq0 - Fbh[64 * c.lane + 63] < -150.f);
;     return __builtin_amdgcn_readfirstlane(__popcll(__ballot(cnd))) & ~1;
; }
; __device__ __forceinline__ unsigned attn_skips(const Ctx& c, int l) {
;     unsigned pk = 0u;
; #pragma unroll
;     for (int i = 0; i < 4; ++i) { int b, h, qb; unit_of(c.vcu, i, b, h, qb); pk |= (unsigned)attn_skip(c, l, b, h, qb) << (8 * i); }
.LBB0_95:
	s_or_b64 exec, exec, s[42:43]
	s_xor_b32 s20, s16, 0xf00
	s_add_i32 s21, s20, 0x100
	v_cndmask_b32_e64 v0, 0, 1, s[40:41]
	s_lshr_b32 s21, s21, 6
	v_cmp_ne_u32_e32 vcc, 0, v0
	s_add_i32 s21, s21, -4
	s_bcnt1_i32_b64 s12, vcc
	v_cmp_gt_u32_e32 vcc, s21, v200
	s_mov_b64 s[40:41], 0
	s_mov_b64 s[38:39], 0
	s_and_saveexec_b64 s[42:43], vcc
	s_mov_b32 s48, 0x3fb8aa3b
	s_mov_b32 s49, 0xc2ce8ed0
	s_cbranch_execz .LBB0_97
	s_or_b32 s44, s13, s6
	s_lshl_b32 s38, s44, 1
	s_ashr_i32 s39, s38, 31
	s_lshl_b64 s[38:39], s[38:39], 2
	s_add_u32 s38, s23, s38
	s_addc_u32 s39, s92, s39
	s_waitcnt lgkmcnt(0)
	s_waitcnt vmcnt(0)
	v_mov_b32_e32 v0, v184
	v_mov_b32_e32 v1, v185
	s_ashr_i32 s45, s44, 31
	s_waitcnt vmcnt(0)
	v_mul_f32_e32 v0, v0, v1
	v_cmp_gt_f32_e32 vcc, s87, v0
	v_mul_f32_e32 v1, 0x4f800000, v0
	s_nop 0
	v_cndmask_b32_e32 v0, v0, v1, vcc
	v_sqrt_f32_e32 v1, v0
	s_nop 0
	v_add_u32_e32 v2, -1, v1
	v_fma_f32 v3, -v2, v1, v0
	v_cmp_ge_f32_e64 s[38:39], 0, v3
	v_add_u32_e32 v3, 1, v1
	s_nop 0
	v_cndmask_b32_e64 v2, v1, v2, s[38:39]
	v_fma_f32 v1, -v3, v1, v0
	v_cmp_lt_f32_e64 s[38:39], 0, v1
	s_nop 1
	v_cndmask_b32_e64 v1, v2, v3, s[38:39]
	s_lshl_b64 s[38:39], s[44:45], 14
	v_mul_f32_e32 v2, 0x37800000, v1
	s_add_u32 s38, s4, s38
	v_cndmask_b32_e32 v1, v1, v2, vcc
	v_cmp_class_f32_e32 vcc, v0, v213
	s_addc_u32 s39, s5, s39
	s_lshl_b32 s13, s20, 2
	v_cndmask_b32_e32 v0, v1, v0, vcc
	v_mov_b32_e32 v1, s13
	s_waitcnt vmcnt(0)
	v_mov_b32_e32 v1, v192
	s_waitcnt vmcnt(0)
	v_fmac_f32_e32 v1, 2.0, v0
	s_waitcnt vmcnt(0)
	v_mov_b32_e32 v0, v188
	s_waitcnt vmcnt(0)
	v_sub_f32_e32 v0, v1, v0
	v_cmp_gt_f32_e32 vcc, s93, v0
	s_and_b64 s[38:39], vcc, exec
.LBB0_97:
	s_or_b64 exec, exec, s[42:43]
	s_xor_b32 s16, s16, 0x700
	s_add_i32 s20, s16, 0x100
	v_cndmask_b32_e64 v0, 0, 1, s[38:39]
	s_lshr_b32 s20, s20, 6
	v_cmp_ne_u32_e32 vcc, 0, v0
	s_add_i32 s20, s20, -4
	s_bcnt1_i32_b64 s13, vcc
	v_cmp_gt_u32_e32 vcc, s20, v200
	s_and_saveexec_b64 s[42:43], vcc
	s_cbranch_execz .LBB0_99
	s_or_b32 s40, s17, s6
	s_lshl_b32 s20, s40, 1
	s_ashr_i32 s21, s20, 31
	s_lshl_b64 s[20:21], s[20:21], 2
	s_add_u32 s20, s23, s20
	s_addc_u32 s21, s92, s21
	s_waitcnt lgkmcnt(0)
	s_waitcnt vmcnt(0)
	v_mov_b32_e32 v0, v186
	v_mov_b32_e32 v1, v187
	s_ashr_i32 s41, s40, 31
	s_lshl_b64 s[20:21], s[40:41], 14
	s_add_u32 s20, s4, s20
	s_addc_u32 s21, s5, s21
	s_lshl_b32 s6, s16, 2
	s_waitcnt vmcnt(0)
	v_mul_f32_e32 v0, v0, v1
	v_cmp_gt_f32_e32 vcc, s87, v0
	v_mul_f32_e32 v1, 0x4f800000, v0
	s_nop 0
	v_cndmask_b32_e32 v0, v0, v1, vcc
	v_sqrt_f32_e32 v1, v0
	s_nop 0
	v_add_u32_e32 v2, -1, v1
	v_fma_f32 v3, -v2, v1, v0
	v_cmp_ge_f32_e64 s[38:39], 0, v3
	v_add_u32_e32 v3, 1, v1
	s_nop 0
	v_cndmask_b32_e64 v2, v1, v2, s[38:39]
	v_fma_f32 v1, -v3, v1, v0
	v_cmp_lt_f32_e64 s[38:39], 0, v1
	s_nop 1
	v_cndmask_b32_e64 v1, v2, v3, s[38:39]
	v_mul_f32_e32 v2, 0x37800000, v1
	v_cndmask_b32_e32 v1, v1, v2, vcc
	v_cmp_class_f32_e32 vcc, v0, v213
	s_nop 1
	v_cndmask_b32_e32 v0, v1, v0, vcc
	v_mov_b32_e32 v1, s6
	s_waitcnt vmcnt(0)
	v_mov_b32_e32 v1, v193
	s_waitcnt vmcnt(0)
	v_fmac_f32_e32 v1, 2.0, v0
	s_waitcnt vmcnt(0)
	v_mov_b32_e32 v0, v189
	s_waitcnt vmcnt(0)
	v_sub_f32_e32 v0, v1, v0
	v_cmp_gt_f32_e32 vcc, s93, v0
	s_and_b64 s[40:41], vcc, exec
